# RET sample-state stream: 16 loads in flight per thread with counted vmcnt instead of load-wait-store per step
# speedup vs baseline: 1.0277x; 1.0277x over previous
; #define LAS __attribute__((address_space(3)))
; __device__ __forceinline__ void ph_ret_fast(const Params& p, int jl, LAS unsigned char* lds, int tid, int lane, int wave) {
;     ...
;             f32x4 oacc = (f32x4){0.f, 0.f, 0.f, 0.f};
; #pragma unroll 8
;             for (int k = 0; k < 64; ++k) { const int d = dq + 4 * k;
;                 const f32x4 sv = __builtin_nontemporal_load((const f32x4*)(sin_ + (size_t)d * RDV));
;                 const f32x4 sn = sv * gamma + v4 * sk[d];
;                 oacc += sn * sq[d];
;                 __builtin_nontemporal_store(sn, (f32x4*)(sout + (size_t)d * RDV)); }
;             *(LAS f32x4*)(red + dq * 512 + 4 * e4) = oacc;
.LBB0_461:
	v_mov_b32_e32 v13, v12
	s_mov_b32 s10, 0x6540000
	s_mov_b32 s11, 0
	s_mov_b64 s[12:13], 0x2000
	s_mov_b32 s2, 0
	v_lshl_add_u64 v[20:21], v[20:21], 0, s[10:11]
	global_load_dwordx4 v[136:139], v[22:23], off nt
	v_lshl_add_u64 v[22:23], v[22:23], 0, s[12:13]
	global_load_dwordx4 v[140:143], v[22:23], off nt
	v_lshl_add_u64 v[22:23], v[22:23], 0, s[12:13]
	global_load_dwordx4 v[144:147], v[22:23], off nt
	v_lshl_add_u64 v[22:23], v[22:23], 0, s[12:13]
	global_load_dwordx4 v[148:151], v[22:23], off nt
	v_lshl_add_u64 v[22:23], v[22:23], 0, s[12:13]
	global_load_dwordx4 v[152:155], v[22:23], off nt
	v_lshl_add_u64 v[22:23], v[22:23], 0, s[12:13]
	global_load_dwordx4 v[156:159], v[22:23], off nt
	v_lshl_add_u64 v[22:23], v[22:23], 0, s[12:13]
	global_load_dwordx4 v[160:163], v[22:23], off nt
	v_lshl_add_u64 v[22:23], v[22:23], 0, s[12:13]
	global_load_dwordx4 v[208:211], v[22:23], off nt
	v_lshl_add_u64 v[22:23], v[22:23], 0, s[12:13]
.Lrs_loop:
	global_load_dwordx4 v[212:215], v[22:23], off nt
	v_lshl_add_u64 v[22:23], v[22:23], 0, s[12:13]
	global_load_dwordx4 v[216:219], v[22:23], off nt
	v_lshl_add_u64 v[22:23], v[22:23], 0, s[12:13]
	global_load_dwordx4 v[240:243], v[22:23], off nt
	v_lshl_add_u64 v[22:23], v[22:23], 0, s[12:13]
	global_load_dwordx4 v[244:247], v[22:23], off nt
	v_lshl_add_u64 v[22:23], v[22:23], 0, s[12:13]
	global_load_dwordx4 v[248:251], v[22:23], off nt
	v_lshl_add_u64 v[22:23], v[22:23], 0, s[12:13]
	global_load_dwordx4 v[234:237], v[22:23], off nt
	v_lshl_add_u64 v[22:23], v[22:23], 0, s[12:13]
	global_load_dwordx4 v[90:93], v[22:23], off nt
	v_lshl_add_u64 v[22:23], v[22:23], 0, s[12:13]
	global_load_dwordx4 v[94:97], v[22:23], off nt
	v_lshl_add_u64 v[22:23], v[22:23], 0, s[12:13]
	v_add_u32_e32 v24, 0x400, v35
	ds_read2_b32 v[46:47], v24 offset0:0 offset1:4
	ds_read2_b32 v[48:49], v24 offset0:8 offset1:12
	ds_read2_b32 v[50:51], v24 offset0:16 offset1:20
	ds_read2_b32 v[52:53], v24 offset0:24 offset1:28
	ds_read2_b32 v[36:37], v35 offset0:0 offset1:4
	ds_read2_b32 v[38:39], v35 offset0:8 offset1:12
	ds_read2_b32 v[40:41], v35 offset0:16 offset1:20
	ds_read2_b32 v[42:43], v35 offset0:24 offset1:28
	v_add_u32_e32 v35, 0x80, v35
	s_waitcnt lgkmcnt(0)
	s_waitcnt vmcnt(15)
	v_pk_mul_f32 v[28:29], v[46:47], v[16:17] op_sel_hi:[0,1]
	v_pk_mul_f32 v[44:45], v[46:47], v[14:15] op_sel_hi:[0,1]
	v_pk_fma_f32 v[138:139], v[12:13], v[138:139], v[28:29]
	v_pk_fma_f32 v[136:137], v[18:19], v[136:137], v[44:45]
	v_pk_fma_f32 v[2:3], v[36:37], v[136:137], v[2:3] op_sel_hi:[0,1,1]
	v_pk_fma_f32 v[4:5], v[36:37], v[138:139], v[4:5] op_sel_hi:[0,1,1]
	global_store_dwordx4 v[20:21], v[136:139], off nt
	v_lshl_add_u64 v[20:21], v[20:21], 0, s[12:13]
	s_waitcnt vmcnt(15)
	v_pk_mul_f32 v[28:29], v[46:47], v[16:17] op_sel:[1,0] op_sel_hi:[1,1]
	v_pk_mul_f32 v[44:45], v[46:47], v[14:15] op_sel:[1,0] op_sel_hi:[1,1]
	v_pk_fma_f32 v[142:143], v[12:13], v[142:143], v[28:29]
	v_pk_fma_f32 v[140:141], v[18:19], v[140:141], v[44:45]
	v_pk_fma_f32 v[2:3], v[36:37], v[140:141], v[2:3] op_sel:[1,0,0] op_sel_hi:[1,1,1]
	v_pk_fma_f32 v[4:5], v[36:37], v[142:143], v[4:5] op_sel:[1,0,0] op_sel_hi:[1,1,1]
	global_store_dwordx4 v[20:21], v[140:143], off nt
	v_lshl_add_u64 v[20:21], v[20:21], 0, s[12:13]
	s_waitcnt vmcnt(15)
	v_pk_mul_f32 v[28:29], v[48:49], v[16:17] op_sel_hi:[0,1]
	v_pk_mul_f32 v[44:45], v[48:49], v[14:15] op_sel_hi:[0,1]
	v_pk_fma_f32 v[146:147], v[12:13], v[146:147], v[28:29]
	v_pk_fma_f32 v[144:145], v[18:19], v[144:145], v[44:45]
	v_pk_fma_f32 v[2:3], v[38:39], v[144:145], v[2:3] op_sel_hi:[0,1,1]
	v_pk_fma_f32 v[4:5], v[38:39], v[146:147], v[4:5] op_sel_hi:[0,1,1]
	global_store_dwordx4 v[20:21], v[144:147], off nt
	v_lshl_add_u64 v[20:21], v[20:21], 0, s[12:13]
	s_waitcnt vmcnt(15)
	v_pk_mul_f32 v[28:29], v[48:49], v[16:17] op_sel:[1,0] op_sel_hi:[1,1]
	v_pk_mul_f32 v[44:45], v[48:49], v[14:15] op_sel:[1,0] op_sel_hi:[1,1]
	v_pk_fma_f32 v[150:151], v[12:13], v[150:151], v[28:29]
	v_pk_fma_f32 v[148:149], v[18:19], v[148:149], v[44:45]
	v_pk_fma_f32 v[2:3], v[38:39], v[148:149], v[2:3] op_sel:[1,0,0] op_sel_hi:[1,1,1]
	v_pk_fma_f32 v[4:5], v[38:39], v[150:151], v[4:5] op_sel:[1,0,0] op_sel_hi:[1,1,1]
	global_store_dwordx4 v[20:21], v[148:151], off nt
	v_lshl_add_u64 v[20:21], v[20:21], 0, s[12:13]
	s_waitcnt vmcnt(15)
	v_pk_mul_f32 v[28:29], v[50:51], v[16:17] op_sel_hi:[0,1]
	v_pk_mul_f32 v[44:45], v[50:51], v[14:15] op_sel_hi:[0,1]
	v_pk_fma_f32 v[154:155], v[12:13], v[154:155], v[28:29]
	v_pk_fma_f32 v[152:153], v[18:19], v[152:153], v[44:45]
	v_pk_fma_f32 v[2:3], v[40:41], v[152:153], v[2:3] op_sel_hi:[0,1,1]
	v_pk_fma_f32 v[4:5], v[40:41], v[154:155], v[4:5] op_sel_hi:[0,1,1]
	global_store_dwordx4 v[20:21], v[152:155], off nt
	v_lshl_add_u64 v[20:21], v[20:21], 0, s[12:13]
	s_waitcnt vmcnt(15)
	v_pk_mul_f32 v[28:29], v[50:51], v[16:17] op_sel:[1,0] op_sel_hi:[1,1]
	v_pk_mul_f32 v[44:45], v[50:51], v[14:15] op_sel:[1,0] op_sel_hi:[1,1]
	v_pk_fma_f32 v[158:159], v[12:13], v[158:159], v[28:29]
	v_pk_fma_f32 v[156:157], v[18:19], v[156:157], v[44:45]
	v_pk_fma_f32 v[2:3], v[40:41], v[156:157], v[2:3] op_sel:[1,0,0] op_sel_hi:[1,1,1]
	v_pk_fma_f32 v[4:5], v[40:41], v[158:159], v[4:5] op_sel:[1,0,0] op_sel_hi:[1,1,1]
	global_store_dwordx4 v[20:21], v[156:159], off nt
	v_lshl_add_u64 v[20:21], v[20:21], 0, s[12:13]
	s_waitcnt vmcnt(15)
	v_pk_mul_f32 v[28:29], v[52:53], v[16:17] op_sel_hi:[0,1]
	v_pk_mul_f32 v[44:45], v[52:53], v[14:15] op_sel_hi:[0,1]
	v_pk_fma_f32 v[162:163], v[12:13], v[162:163], v[28:29]
	v_pk_fma_f32 v[160:161], v[18:19], v[160:161], v[44:45]
	v_pk_fma_f32 v[2:3], v[42:43], v[160:161], v[2:3] op_sel_hi:[0,1,1]
	v_pk_fma_f32 v[4:5], v[42:43], v[162:163], v[4:5] op_sel_hi:[0,1,1]
	global_store_dwordx4 v[20:21], v[160:163], off nt
	v_lshl_add_u64 v[20:21], v[20:21], 0, s[12:13]
	s_waitcnt vmcnt(15)
	v_pk_mul_f32 v[28:29], v[52:53], v[16:17] op_sel:[1,0] op_sel_hi:[1,1]
	v_pk_mul_f32 v[44:45], v[52:53], v[14:15] op_sel:[1,0] op_sel_hi:[1,1]
	v_pk_fma_f32 v[210:211], v[12:13], v[210:211], v[28:29]
	v_pk_fma_f32 v[208:209], v[18:19], v[208:209], v[44:45]
	v_pk_fma_f32 v[2:3], v[42:43], v[208:209], v[2:3] op_sel:[1,0,0] op_sel_hi:[1,1,1]
	v_pk_fma_f32 v[4:5], v[42:43], v[210:211], v[4:5] op_sel:[1,0,0] op_sel_hi:[1,1,1]
	global_store_dwordx4 v[20:21], v[208:211], off nt
	v_lshl_add_u64 v[20:21], v[20:21], 0, s[12:13]
	s_cmp_eq_u32 s2, 3
	s_cbranch_scc1 .Lrs_skipa
; #define LAS __attribute__((address_space(3)))
; __device__ __forceinline__ void st_bf4(bf16* q, const f32x4 v) { v2u w; w.x = cvt_pk_bf16(v.x, v.y); w.y = cvt_pk_bf16(v.z, v.w); *(v2u*)q = w; }
; __device__ __forceinline__ void ph_ret_fast(const Params& p, int jl, LAS unsigned char* lds, int tid, int lane, int wave) {
;     ...
; #pragma unroll 8
;             for (int k = 0; k < 64; ++k) { const int d = dq + 4 * k;
;                 const f32x4 sv = __builtin_nontemporal_load((const f32x4*)(sin_ + (size_t)d * RDV));
;                 const f32x4 sn = sv * gamma + v4 * sk[d];
;                 oacc += sn * sq[d];
;                 __builtin_nontemporal_store(sn, (f32x4*)(sout + (size_t)d * RDV)); }
;             *(LAS f32x4*)(red + dq * 512 + 4 * e4) = oacc;
;             __syncthreads();
;             if (dq == 0) { const f32x4 r = (*(LAS f32x4*)(red + 4 * e4) + *(LAS f32x4*)(red + 512 + 4 * e4)) + (*(LAS f32x4*)(red + 1024 + 4 * e4) + *(LAS f32x4*)(red + 1536 + 4 * e4));
;                 st_bf4(O + (size_t)row * RV + 512 * h + 4 * e4, r); }
	global_load_dwordx4 v[136:139], v[22:23], off nt
	v_lshl_add_u64 v[22:23], v[22:23], 0, s[12:13]
	global_load_dwordx4 v[140:143], v[22:23], off nt
	v_lshl_add_u64 v[22:23], v[22:23], 0, s[12:13]
	global_load_dwordx4 v[144:147], v[22:23], off nt
	v_lshl_add_u64 v[22:23], v[22:23], 0, s[12:13]
	global_load_dwordx4 v[148:151], v[22:23], off nt
	v_lshl_add_u64 v[22:23], v[22:23], 0, s[12:13]
	global_load_dwordx4 v[152:155], v[22:23], off nt
	v_lshl_add_u64 v[22:23], v[22:23], 0, s[12:13]
	global_load_dwordx4 v[156:159], v[22:23], off nt
	v_lshl_add_u64 v[22:23], v[22:23], 0, s[12:13]
	global_load_dwordx4 v[160:163], v[22:23], off nt
	v_lshl_add_u64 v[22:23], v[22:23], 0, s[12:13]
	global_load_dwordx4 v[208:211], v[22:23], off nt
	v_lshl_add_u64 v[22:23], v[22:23], 0, s[12:13]
.Lrs_skipa:
	v_add_u32_e32 v24, 0x400, v35
	ds_read2_b32 v[46:47], v24 offset0:0 offset1:4
	ds_read2_b32 v[48:49], v24 offset0:8 offset1:12
	ds_read2_b32 v[50:51], v24 offset0:16 offset1:20
	ds_read2_b32 v[52:53], v24 offset0:24 offset1:28
	ds_read2_b32 v[36:37], v35 offset0:0 offset1:4
	ds_read2_b32 v[38:39], v35 offset0:8 offset1:12
	ds_read2_b32 v[40:41], v35 offset0:16 offset1:20
	ds_read2_b32 v[42:43], v35 offset0:24 offset1:28
	v_add_u32_e32 v35, 0x80, v35
	s_waitcnt lgkmcnt(0)
	s_waitcnt vmcnt(15)
	v_pk_mul_f32 v[28:29], v[46:47], v[16:17] op_sel_hi:[0,1]
	v_pk_mul_f32 v[44:45], v[46:47], v[14:15] op_sel_hi:[0,1]
	v_pk_fma_f32 v[214:215], v[12:13], v[214:215], v[28:29]
	v_pk_fma_f32 v[212:213], v[18:19], v[212:213], v[44:45]
	v_pk_fma_f32 v[2:3], v[36:37], v[212:213], v[2:3] op_sel_hi:[0,1,1]
	v_pk_fma_f32 v[4:5], v[36:37], v[214:215], v[4:5] op_sel_hi:[0,1,1]
	global_store_dwordx4 v[20:21], v[212:215], off nt
	v_lshl_add_u64 v[20:21], v[20:21], 0, s[12:13]
	s_waitcnt vmcnt(15)
	v_pk_mul_f32 v[28:29], v[46:47], v[16:17] op_sel:[1,0] op_sel_hi:[1,1]
	v_pk_mul_f32 v[44:45], v[46:47], v[14:15] op_sel:[1,0] op_sel_hi:[1,1]
	v_pk_fma_f32 v[218:219], v[12:13], v[218:219], v[28:29]
	v_pk_fma_f32 v[216:217], v[18:19], v[216:217], v[44:45]
	v_pk_fma_f32 v[2:3], v[36:37], v[216:217], v[2:3] op_sel:[1,0,0] op_sel_hi:[1,1,1]
	v_pk_fma_f32 v[4:5], v[36:37], v[218:219], v[4:5] op_sel:[1,0,0] op_sel_hi:[1,1,1]
	global_store_dwordx4 v[20:21], v[216:219], off nt
	v_lshl_add_u64 v[20:21], v[20:21], 0, s[12:13]
	s_waitcnt vmcnt(15)
	v_pk_mul_f32 v[28:29], v[48:49], v[16:17] op_sel_hi:[0,1]
	v_pk_mul_f32 v[44:45], v[48:49], v[14:15] op_sel_hi:[0,1]
	v_pk_fma_f32 v[242:243], v[12:13], v[242:243], v[28:29]
	v_pk_fma_f32 v[240:241], v[18:19], v[240:241], v[44:45]
	v_pk_fma_f32 v[2:3], v[38:39], v[240:241], v[2:3] op_sel_hi:[0,1,1]
	v_pk_fma_f32 v[4:5], v[38:39], v[242:243], v[4:5] op_sel_hi:[0,1,1]
	global_store_dwordx4 v[20:21], v[240:243], off nt
	v_lshl_add_u64 v[20:21], v[20:21], 0, s[12:13]
	s_waitcnt vmcnt(15)
	v_pk_mul_f32 v[28:29], v[48:49], v[16:17] op_sel:[1,0] op_sel_hi:[1,1]
	v_pk_mul_f32 v[44:45], v[48:49], v[14:15] op_sel:[1,0] op_sel_hi:[1,1]
	v_pk_fma_f32 v[246:247], v[12:13], v[246:247], v[28:29]
	v_pk_fma_f32 v[244:245], v[18:19], v[244:245], v[44:45]
	v_pk_fma_f32 v[2:3], v[38:39], v[244:245], v[2:3] op_sel:[1,0,0] op_sel_hi:[1,1,1]
	v_pk_fma_f32 v[4:5], v[38:39], v[246:247], v[4:5] op_sel:[1,0,0] op_sel_hi:[1,1,1]
	global_store_dwordx4 v[20:21], v[244:247], off nt
	v_lshl_add_u64 v[20:21], v[20:21], 0, s[12:13]
	s_waitcnt vmcnt(15)
	v_pk_mul_f32 v[28:29], v[50:51], v[16:17] op_sel_hi:[0,1]
	v_pk_mul_f32 v[44:45], v[50:51], v[14:15] op_sel_hi:[0,1]
	v_pk_fma_f32 v[250:251], v[12:13], v[250:251], v[28:29]
	v_pk_fma_f32 v[248:249], v[18:19], v[248:249], v[44:45]
	v_pk_fma_f32 v[2:3], v[40:41], v[248:249], v[2:3] op_sel_hi:[0,1,1]
	v_pk_fma_f32 v[4:5], v[40:41], v[250:251], v[4:5] op_sel_hi:[0,1,1]
	global_store_dwordx4 v[20:21], v[248:251], off nt
	v_lshl_add_u64 v[20:21], v[20:21], 0, s[12:13]
	s_waitcnt vmcnt(15)
	v_pk_mul_f32 v[28:29], v[50:51], v[16:17] op_sel:[1,0] op_sel_hi:[1,1]
	v_pk_mul_f32 v[44:45], v[50:51], v[14:15] op_sel:[1,0] op_sel_hi:[1,1]
	v_pk_fma_f32 v[236:237], v[12:13], v[236:237], v[28:29]
	v_pk_fma_f32 v[234:235], v[18:19], v[234:235], v[44:45]
	v_pk_fma_f32 v[2:3], v[40:41], v[234:235], v[2:3] op_sel:[1,0,0] op_sel_hi:[1,1,1]
	v_pk_fma_f32 v[4:5], v[40:41], v[236:237], v[4:5] op_sel:[1,0,0] op_sel_hi:[1,1,1]
	global_store_dwordx4 v[20:21], v[234:237], off nt
	v_lshl_add_u64 v[20:21], v[20:21], 0, s[12:13]
	s_waitcnt vmcnt(15)
	v_pk_mul_f32 v[28:29], v[52:53], v[16:17] op_sel_hi:[0,1]
	v_pk_mul_f32 v[44:45], v[52:53], v[14:15] op_sel_hi:[0,1]
	v_pk_fma_f32 v[92:93], v[12:13], v[92:93], v[28:29]
	v_pk_fma_f32 v[90:91], v[18:19], v[90:91], v[44:45]
	v_pk_fma_f32 v[2:3], v[42:43], v[90:91], v[2:3] op_sel_hi:[0,1,1]
	v_pk_fma_f32 v[4:5], v[42:43], v[92:93], v[4:5] op_sel_hi:[0,1,1]
	global_store_dwordx4 v[20:21], v[90:93], off nt
	v_lshl_add_u64 v[20:21], v[20:21], 0, s[12:13]
	s_waitcnt vmcnt(15)
	v_pk_mul_f32 v[28:29], v[52:53], v[16:17] op_sel:[1,0] op_sel_hi:[1,1]
	v_pk_mul_f32 v[44:45], v[52:53], v[14:15] op_sel:[1,0] op_sel_hi:[1,1]
	v_pk_fma_f32 v[96:97], v[12:13], v[96:97], v[28:29]
	v_pk_fma_f32 v[94:95], v[18:19], v[94:95], v[44:45]
	v_pk_fma_f32 v[2:3], v[42:43], v[94:95], v[2:3] op_sel:[1,0,0] op_sel_hi:[1,1,1]
	v_pk_fma_f32 v[4:5], v[42:43], v[96:97], v[4:5] op_sel:[1,0,0] op_sel_hi:[1,1,1]
	global_store_dwordx4 v[20:21], v[94:97], off nt
	v_lshl_add_u64 v[20:21], v[20:21], 0, s[12:13]
	s_add_i32 s2, s2, 1
	s_cmp_eq_u32 s2, 4
	s_cbranch_scc0 .Lrs_loop
	ds_write_b128 v32, v[2:5] offset:2048
	s_waitcnt lgkmcnt(0)
	s_barrier
	s_and_saveexec_b64 s[2:3], s[6:7]
	s_cbranch_execz .LBB0_459
	ds_read_b128 v[2:5], v31 offset:2048
	ds_read_b128 v[12:15], v31 offset:4096
	s_lshl_b64 s[0:1], s[0:1], 1
	v_readlane_b32 s10, v252, 54
	v_readlane_b32 s11, v252, 55
	s_add_u32 s0, s10, s0
	s_waitcnt lgkmcnt(0)
	v_pk_add_f32 v[16:17], v[4:5], v[14:15]
	v_pk_add_f32 v[18:19], v[2:3], v[12:13]
	ds_read_b128 v[2:5], v31 offset:6144
	ds_read_b128 v[12:15], v31 offset:8192
	s_addc_u32 s1, s11, s1
	s_lshl_b32 s9, s9, 1
	s_add_u32 s0, s0, s9
	s_addc_u32 s1, s1, 0
	s_waitcnt lgkmcnt(0)
	v_pk_add_f32 v[2:3], v[2:3], v[12:13]
	v_pk_add_f32 v[4:5], v[4:5], v[14:15]
	v_pk_add_f32 v[2:3], v[18:19], v[2:3]
	v_pk_add_f32 v[4:5], v[16:17], v[4:5]
	v_cvt_pk_bf16_f32 v2, v2, v3
	s_nop 0
	v_cvt_pk_bf16_f32 v3, v4, v5
	global_store_dwordx2 v34, v[2:3], s[0:1]
	s_branch .LBB0_459
